# P0: W_out items also issue all 32 weight loads up front (scalar-base addressing, counted waits)
# speedup vs baseline: 1.0314x; 1.0099x over previous
; #define DUPREP(k) for (int rep_ = 0; rep_ < 1 + ((MK_DUP >> (k)) & 1); ++rep_)
; #define LAS __attribute__((address_space(3)))
; __device__ __forceinline__ void p0_transpose_item(const float* W, int K, int N, bf16_t* WT, LAS float* scr, int item, int lane, const float* kscale) {
;     const int nblk = N / 32, kb = item / nblk, nb = item % nblk, k0 = 64 * kb, n0 = 32 * nb;
; #pragma unroll 8
;     for (int i = 0; i < 32; ++i) { const int kk = 2 * i + (lane >> 5); scr[kk * 33 + (lane & 31)] = W[(size_t)(k0 + kk) * N + n0 + (lane & 31)] * (kscale ? kscale[k0 + kk] : 1.0f); }
; __global__ void __launch_bounds__(512, 2) mk_fwd(Params p) {
;     ...
;             DUPREP(0) for (int it = gw; it < DEPTH * IL; it += NGW) {
;                 const int l = it / IL, r = it % IL;
;                 if (r < I1) p0_transpose_item(p.w_in + (size_t)l * DM * DIN, DM, DIN, W1T + (size_t)l * DIN * DM, scr, r, lane, p.norm_w + (size_t)l * DM);
;                 else p0_transpose_item(p.w_out + (size_t)l * DM * DM, DM, DM, W2T + (size_t)l * DM * DM, scr, r - I1, lane, nullptr);
.LBB0_226:
	s_mul_hi_i32 s0, s4, 0x78787879
	s_lshr_b32 s1, s0, 31
	s_ashr_i32 s0, s0, 12
	s_add_i32 s2, s0, s1
	s_mul_i32 s0, s2, 0x2200
	s_sub_i32 s5, s4, s0
	s_ashr_i32 s3, s2, 31
	s_cmpk_gt_i32 s5, 0x19ff
	s_mov_b64 s[0:1], -1
	s_cbranch_scc0 .LBB0_230
	s_lshl_b64 s[0:1], s[2:3], 22
	s_lshl_b64 s[6:7], s[2:3], 24
	s_add_u32 s8, s66, s6
	s_addc_u32 s9, s67, s7
	s_add_i32 s6, s5, 0xe600
	s_and_b32 s7, s6, 0xffc0
	s_lshl_b32 s6, s5, 5
	s_and_b32 s6, s6, 0x7e0
	s_lshl_b32 s10, s6, 2
	s_add_u32 s8, s8, s10
	s_addc_u32 s9, s9, 0
	v_mov_b32_e32 v13, v1
	v_lshl_add_u64 v[14:15], s[8:9], 0, v[12:13]
	v_or_b32_e32 v5, s7, v3
	v_or_b32_e32 v16, s7, v4
	s_lshl_b32 s10, s7, 13
	s_add_u32 s8, s8, s10
	s_addc_u32 s9, s9, 0
	v_lshlrev_b32_e32 v47, 13, v4
	v_add_u32_e32 v47, v47, v12
	global_load_dword v100, v47, s[8:9]
	s_add_u32 s8, s8, 0x4000
	s_addc_u32 s9, s9, 0
	global_load_dword v101, v47, s[8:9]
	s_add_u32 s8, s8, 0x4000
	s_addc_u32 s9, s9, 0
	global_load_dword v102, v47, s[8:9]
	s_add_u32 s8, s8, 0x4000
	s_addc_u32 s9, s9, 0
	global_load_dword v103, v47, s[8:9]
	s_add_u32 s8, s8, 0x4000
	s_addc_u32 s9, s9, 0
	global_load_dword v104, v47, s[8:9]
	s_add_u32 s8, s8, 0x4000
	s_addc_u32 s9, s9, 0
	global_load_dword v105, v47, s[8:9]
	s_add_u32 s8, s8, 0x4000
	s_addc_u32 s9, s9, 0
	global_load_dword v106, v47, s[8:9]
	s_add_u32 s8, s8, 0x4000
	s_addc_u32 s9, s9, 0
	global_load_dword v107, v47, s[8:9]
	s_add_u32 s8, s8, 0x4000
	s_addc_u32 s9, s9, 0
	global_load_dword v108, v47, s[8:9]
	s_add_u32 s8, s8, 0x4000
	s_addc_u32 s9, s9, 0
	global_load_dword v109, v47, s[8:9]
	s_add_u32 s8, s8, 0x4000
	s_addc_u32 s9, s9, 0
	global_load_dword v110, v47, s[8:9]
	s_add_u32 s8, s8, 0x4000
	s_addc_u32 s9, s9, 0
	global_load_dword v111, v47, s[8:9]
	s_add_u32 s8, s8, 0x4000
	s_addc_u32 s9, s9, 0
	global_load_dword v112, v47, s[8:9]
	s_add_u32 s8, s8, 0x4000
	s_addc_u32 s9, s9, 0
	global_load_dword v113, v47, s[8:9]
	s_add_u32 s8, s8, 0x4000
	s_addc_u32 s9, s9, 0
	global_load_dword v114, v47, s[8:9]
	s_add_u32 s8, s8, 0x4000
	s_addc_u32 s9, s9, 0
	global_load_dword v115, v47, s[8:9]
	s_add_u32 s8, s8, 0x4000
	s_addc_u32 s9, s9, 0
	global_load_dword v116, v47, s[8:9]
	s_add_u32 s8, s8, 0x4000
	s_addc_u32 s9, s9, 0
	global_load_dword v117, v47, s[8:9]
	s_add_u32 s8, s8, 0x4000
	s_addc_u32 s9, s9, 0
	global_load_dword v118, v47, s[8:9]
	s_add_u32 s8, s8, 0x4000
	s_addc_u32 s9, s9, 0
	global_load_dword v119, v47, s[8:9]
	s_add_u32 s8, s8, 0x4000
	s_addc_u32 s9, s9, 0
	global_load_dword v120, v47, s[8:9]
	s_add_u32 s8, s8, 0x4000
	s_addc_u32 s9, s9, 0
	global_load_dword v121, v47, s[8:9]
	s_add_u32 s8, s8, 0x4000
	s_addc_u32 s9, s9, 0
	global_load_dword v122, v47, s[8:9]
	s_add_u32 s8, s8, 0x4000
	s_addc_u32 s9, s9, 0
	global_load_dword v123, v47, s[8:9]
	s_add_u32 s8, s8, 0x4000
	s_addc_u32 s9, s9, 0
	global_load_dword v124, v47, s[8:9]
	s_add_u32 s8, s8, 0x4000
	s_addc_u32 s9, s9, 0
	global_load_dword v125, v47, s[8:9]
	s_add_u32 s8, s8, 0x4000
	s_addc_u32 s9, s9, 0
	global_load_dword v126, v47, s[8:9]
	s_add_u32 s8, s8, 0x4000
	s_addc_u32 s9, s9, 0
	global_load_dword v127, v47, s[8:9]
	s_add_u32 s8, s8, 0x4000
	s_addc_u32 s9, s9, 0
	global_load_dword v128, v47, s[8:9]
	s_add_u32 s8, s8, 0x4000
	s_addc_u32 s9, s9, 0
	global_load_dword v129, v47, s[8:9]
	s_add_u32 s8, s8, 0x4000
	s_addc_u32 s9, s9, 0
	global_load_dword v130, v47, s[8:9]
	s_add_u32 s8, s8, 0x4000
	s_addc_u32 s9, s9, 0
	global_load_dword v131, v47, s[8:9]
	s_waitcnt vmcnt(31)
	ds_write_b32 v39, v100 offset:0
	s_waitcnt vmcnt(30)
	ds_write_b32 v39, v101 offset:264
	s_waitcnt vmcnt(29)
	ds_write_b32 v39, v102 offset:528
	s_waitcnt vmcnt(28)
	ds_write_b32 v39, v103 offset:792
	s_waitcnt vmcnt(27)
	ds_write_b32 v39, v104 offset:1056
	s_waitcnt vmcnt(26)
	ds_write_b32 v39, v105 offset:1320
	s_waitcnt vmcnt(25)
; #define LAS __attribute__((address_space(3)))
; #define LDS_WAIT() asm volatile("s_waitcnt lgkmcnt(0)" ::: "memory")
; __device__ __forceinline__ unsigned pk2(float lo, float hi) { unsigned r; asm("v_cvt_pk_bf16_f32 %0, %1, %2" : "=v"(r) : "v"(lo), "v"(hi)); return r; }
; __device__ __forceinline__ void p0_transpose_item(const float* W, int K, int N, bf16_t* WT, LAS float* scr, int item, int lane, const float* kscale) {
;     ...
;     for (int i = 0; i < 32; ++i) { const int kk = 2 * i + (lane >> 5); scr[kk * 33 + (lane & 31)] = W[(size_t)(k0 + kk) * N + n0 + (lane & 31)] * (kscale ? kscale[k0 + kk] : 1.0f); }
;     LDS_WAIT(); asm volatile("" ::: "memory");
;     const int c = lane & 7;
; #pragma unroll
;     for (int j = 0; j < 4; ++j) { const int n = (lane >> 3) + 8 * j; const LAS float* s = scr + (8 * c) * 33 + n;
;         v4u o; o.x = pk2(s[0 * 33], s[1 * 33]); o.y = pk2(s[2 * 33], s[3 * 33]); o.z = pk2(s[4 * 33], s[5 * 33]); o.w = pk2(s[6 * 33], s[7 * 33]);
;         *(v4u*)(WT + (size_t)(n0 + n) * K + k0 + 8 * c) = o; }
;     LDS_WAIT(); asm volatile("" ::: "memory");
	ds_write_b32 v39, v106 offset:1584
	s_waitcnt vmcnt(24)
	ds_write_b32 v39, v107 offset:1848
	s_waitcnt vmcnt(23)
	ds_write_b32 v39, v108 offset:2112
	s_waitcnt vmcnt(22)
	ds_write_b32 v39, v109 offset:2376
	s_waitcnt vmcnt(21)
	ds_write_b32 v39, v110 offset:2640
	s_waitcnt vmcnt(20)
	ds_write_b32 v39, v111 offset:2904
	s_waitcnt vmcnt(19)
	ds_write_b32 v39, v112 offset:3168
	s_waitcnt vmcnt(18)
	ds_write_b32 v39, v113 offset:3432
	s_waitcnt vmcnt(17)
	ds_write_b32 v39, v114 offset:3696
	s_waitcnt vmcnt(16)
	ds_write_b32 v39, v115 offset:3960
	s_waitcnt vmcnt(15)
	ds_write_b32 v39, v116 offset:4224
	s_waitcnt vmcnt(14)
	ds_write_b32 v39, v117 offset:4488
	s_waitcnt vmcnt(13)
	ds_write_b32 v39, v118 offset:4752
	s_waitcnt vmcnt(12)
	ds_write_b32 v39, v119 offset:5016
	s_waitcnt vmcnt(11)
	ds_write_b32 v39, v120 offset:5280
	s_waitcnt vmcnt(10)
	ds_write_b32 v39, v121 offset:5544
	s_waitcnt vmcnt(9)
	ds_write_b32 v39, v122 offset:5808
	s_waitcnt vmcnt(8)
	ds_write_b32 v39, v123 offset:6072
	s_waitcnt vmcnt(7)
	ds_write_b32 v39, v124 offset:6336
	s_waitcnt vmcnt(6)
	ds_write_b32 v39, v125 offset:6600
	s_waitcnt vmcnt(5)
	ds_write_b32 v39, v126 offset:6864
	s_waitcnt vmcnt(4)
	ds_write_b32 v39, v127 offset:7128
	s_waitcnt vmcnt(3)
	ds_write_b32 v39, v128 offset:7392
	s_waitcnt vmcnt(2)
	ds_write_b32 v39, v129 offset:7656
	s_waitcnt vmcnt(1)
	ds_write_b32 v39, v130 offset:7920
	s_waitcnt vmcnt(0)
	ds_write_b32 v39, v131 offset:8184
	s_lshl_b64 s[0:1], s[0:1], 1
	s_add_u32 s0, s96, s0
	s_waitcnt lgkmcnt(0)
	s_addc_u32 s1, s97, s1
	s_lshl_b32 s7, s7, 1
	s_add_u32 s0, s0, s7
	ds_read2_b32 v[18:19], v9 offset0:33 offset1:41
	ds_read2_b32 v[20:21], v9 offset1:8
	ds_read2_b32 v[22:23], v9 offset0:66 offset1:74
	ds_read2_b32 v[24:25], v9 offset0:99 offset1:107
	ds_read2_b32 v[26:27], v9 offset0:132 offset1:140
	ds_read2_b32 v[28:29], v9 offset0:165 offset1:173
	ds_read2_b32 v[30:31], v9 offset0:198 offset1:206
	ds_read2_b32 v[32:33], v9 offset0:231 offset1:239
	s_addc_u32 s1, s1, 0
	v_lshlrev_b32_e32 v0, 1, v8
	v_lshl_add_u64 v[34:35], s[0:1], 0, v[0:1]
	v_or_b32_e32 v0, s6, v7
	v_lshlrev_b32_e32 v0, 12, v0
	v_lshl_add_u64 v[48:49], v[34:35], 0, v[0:1]
	s_waitcnt lgkmcnt(6)
	v_cvt_pk_bf16_f32 v14, v20, v18
	s_waitcnt lgkmcnt(4)
	v_cvt_pk_bf16_f32 v15, v22, v24
	s_waitcnt lgkmcnt(2)
	v_cvt_pk_bf16_f32 v16, v26, v28
	s_waitcnt lgkmcnt(0)
	v_cvt_pk_bf16_f32 v17, v30, v32
	global_store_dwordx4 v[48:49], v[14:17], off
	v_or_b32_e32 v0, s6, v36
	v_lshlrev_b32_e32 v0, 12, v0
	v_cvt_pk_bf16_f32 v14, v21, v19
	v_cvt_pk_bf16_f32 v15, v23, v25
	v_cvt_pk_bf16_f32 v16, v27, v29
	v_cvt_pk_bf16_f32 v17, v31, v33
	ds_read2_b32 v[20:21], v9 offset0:16 offset1:24
	ds_read2_b32 v[22:23], v9 offset0:49 offset1:57
	ds_read2_b32 v[24:25], v9 offset0:82 offset1:90
	ds_read2_b32 v[26:27], v9 offset0:115 offset1:123
	ds_read2_b32 v[28:29], v9 offset0:148 offset1:156
	ds_read2_b32 v[30:31], v9 offset0:181 offset1:189
	ds_read2_b32 v[32:33], v9 offset0:214 offset1:222
	ds_read2_b32 v[48:49], v9 offset0:247 offset1:255
	v_lshl_add_u64 v[18:19], v[34:35], 0, v[0:1]
	v_or_b32_e32 v0, s6, v37
	v_lshlrev_b32_e32 v0, 12, v0
	global_store_dwordx4 v[18:19], v[14:17], off
	v_lshl_add_u64 v[18:19], v[34:35], 0, v[0:1]
	v_or_b32_e32 v0, s6, v38
	v_lshlrev_b32_e32 v0, 12, v0
	s_waitcnt lgkmcnt(6)
	v_cvt_pk_bf16_f32 v14, v20, v22
	s_waitcnt lgkmcnt(4)
	v_cvt_pk_bf16_f32 v15, v24, v26
	s_waitcnt lgkmcnt(2)
	v_cvt_pk_bf16_f32 v16, v28, v30
	s_waitcnt lgkmcnt(0)
	v_cvt_pk_bf16_f32 v17, v32, v48
	global_store_dwordx4 v[18:19], v[14:17], off
	v_lshl_add_u64 v[18:19], v[34:35], 0, v[0:1]
	s_nop 0
	v_cvt_pk_bf16_f32 v14, v21, v23
	v_cvt_pk_bf16_f32 v15, v25, v27
	v_cvt_pk_bf16_f32 v16, v29, v31
	v_cvt_pk_bf16_f32 v17, v33, v49
	global_store_dwordx4 v[18:19], v[14:17], off
	s_waitcnt lgkmcnt(0)
	s_branch .LBB0_225
